# forget-gate cumulative sums moved from P5 into P6 (workgroups 192..255, idle there, two scans each) beside the compress GEMM
# baseline (speedup 1.0000x reference)
.LBB0_581:
	s_or_b64 exec, exec, s[12:13]
	s_waitcnt vmcnt(0)
	s_waitcnt lgkmcnt(0)
	s_barrier
	s_mov_b64 s[0:1], exec
	v_readlane_b32 s2, v252, 2
	v_readlane_b32 s3, v252, 3
	s_and_b64 s[2:3], s[0:1], s[2:3]
	s_mov_b64 exec, s[2:3]
	s_cbranch_execz .LBB0_636
	s_add_i32 s2, 0, 0x20040
	v_mov_b32_e32 v0, s2
	s_waitcnt vmcnt(0) expcnt(0) lgkmcnt(0)
	ds_read_b32 v2, v0
	s_add_i32 s2, 0, 0x20044
	v_mov_b32_e32 v0, s2
	ds_read_b32 v0, v0
	s_waitcnt lgkmcnt(1)
	v_cmp_ne_u32_e32 vcc, 0, v2
	s_cbranch_vccnz .LBB0_600
	s_add_u32 s4, s88, 0x1000
	s_addc_u32 s5, s89, 0
	s_add_u32 s6, s88, 0x1100
	s_addc_u32 s7, s89, 0
	s_add_u32 s8, s88, 0x1200
	v_readlane_b32 s2, v252, 0
	s_addc_u32 s9, s89, 0
	s_mul_i32 s2, s91, s2
	s_add_u32 s10, s88, 0x1300
	s_mul_i32 s2, s2, s90
	s_addc_u32 s11, s89, 0
	s_mov_b32 s3, 1
	v_mov_b32_e32 v16, 0
	s_branch .LBB0_588

.LBB0_689:
	v_readlane_b32 s2, v252, 4
	v_mov_b32_e32 v26, v230
	v_and_b32_e32 v19, 63, v230
	v_lshrrev_b32_e32 v0, 6, v230
	s_lshr_b32 s2, s2, 3
	s_sub_i32 s2, s2, 0xc0
	s_lshl_b32 s3, s2, 1
	s_cmp_ge_i32 s2, 0
	s_cselect_b64 s[4:5], -1, 0
	v_add_u32_e32 v1, s3, v0
	v_cmp_gt_u32_e32 vcc, 2, v0
	v_mov_b32_e32 v2, 0x80
	s_and_b64 vcc, vcc, s[4:5]
	v_mov_b32_e32 v65, 0
	s_mov_b64 s[6:7], s[92:93]
	v_cndmask_b32_e32 v64, v2, v1, vcc
	s_load_dwordx2 s[0:1], s[6:7], 0xd8
	s_movk_i32 s2, 0x80
	v_cmp_gt_i32_e32 vcc, s2, v64
	s_and_saveexec_b64 s[16:17], vcc
	s_cbranch_execz .Lscan_done
	s_load_dwordx2 s[2:3], s[6:7], 0x58
	v_and_b32_e32 v2, 7, v64
	v_lshlrev_b32_e32 v0, 2, v2
	v_mov_b32_e32 v1, 0
	v_mbcnt_hi_u32_b32 v4, -1, v220
	s_waitcnt lgkmcnt(0)
	v_lshl_add_u64 v[66:67], s[2:3], 0, v[0:1]
	v_lshlrev_b32_e32 v0, 18, v2
	v_lshl_add_u64 v[2:3], s[0:1], 0, v[0:1]
	v_lshlrev_b32_e32 v0, 8, v19
	v_lshl_add_u64 v[0:1], v[2:3], 0, v[0:1]
	s_mov_b64 s[2:3], 0x3aa0000
	v_and_b32_e32 v5, 64, v4
	v_lshl_add_u64 v[68:69], v[0:1], 0, s[2:3]
	v_add_u32_e32 v0, -1, v4
	v_cmp_lt_i32_e32 vcc, v0, v5
	s_ashr_i32 s95, s94, 31
	s_lshl_b64 s[18:19], s[94:95], 14
	v_cndmask_b32_e32 v0, v0, v4, vcc
	v_lshlrev_b32_e32 v78, 2, v0
	v_add_u32_e32 v0, -2, v4
	v_cmp_lt_i32_e64 s[4:5], v0, v5
	v_cmp_eq_u32_e32 vcc, 0, v19
	v_readlane_b32 s87, v252, 5
	v_cndmask_b32_e64 v0, v0, v4, s[4:5]
	v_lshlrev_b32_e32 v79, 2, v0
	v_add_u32_e32 v0, -4, v4
	v_cmp_lt_i32_e64 s[6:7], v0, v5
	v_cmp_gt_u32_e64 s[4:5], 2, v19
	s_mov_b64 s[20:21], 0
	v_cndmask_b32_e64 v0, v0, v4, s[6:7]
	v_lshlrev_b32_e32 v80, 2, v0
	v_add_u32_e32 v0, -8, v4
	v_cmp_lt_i32_e64 s[8:9], v0, v5
	v_cmp_gt_u32_e64 s[6:7], 4, v19
	s_mov_b32 s23, 0x42ce8ed0
	v_cndmask_b32_e64 v0, v0, v4, s[8:9]
	v_lshlrev_b32_e32 v81, 2, v0
	v_add_u32_e32 v0, -16, v4
	v_cmp_lt_i32_e64 s[10:11], v0, v5
	v_cmp_gt_u32_e64 s[8:9], 8, v19
	s_mov_b32 s24, 0xc2b17218
	v_cndmask_b32_e64 v0, v0, v4, s[10:11]
	v_lshlrev_b32_e32 v82, 2, v0
	v_subrev_u32_e32 v0, 32, v4
	v_cmp_lt_i32_e64 s[12:13], v0, v5
	v_cmp_gt_u32_e64 s[10:11], 16, v19
	s_mov_b32 s25, 0x7f800000
	v_cndmask_b32_e64 v0, v0, v4, s[12:13]
	v_lshlrev_b32_e32 v83, 2, v0
	v_lshlrev_b64 v[0:1], 14, v[64:65]
	v_lshl_or_b32 v0, v19, 8, v0
	v_lshl_add_u64 v[0:1], s[0:1], 0, v[0:1]
	s_mov_b64 s[0:1], 0x30a00f0
	v_cmp_gt_u32_e64 s[12:13], 32, v19
	v_lshl_add_u64 v[70:71], v[0:1], 0, s[0:1]
	s_mov_b32 s0, 0xbfb8aa3b
	s_mov_b32 s1, 0xb2a5705f
	v_mov_b32_e32 v65, 0x7f800000
	s_mov_b32 s26, 0x3f2aaaab
	v_mov_b32_e32 v84, 0x3ecc95a3
	s_mov_b32 s27, 0x3f317218
	s_mov_b32 s28, 0x33800000
	s_mov_b32 s22, 0x3fb8aa3b
	s_movk_i32 s29, 0x7f
	v_mov_b32_e32 v72, 0x3f317218

.Lscan_done:
	s_or_b64 exec, exec, s[16:17]
	s_waitcnt vmcnt(0)
	s_waitcnt vmcnt(0) lgkmcnt(0)
	s_barrier
	s_mov_b64 s[0:1], exec
	v_readlane_b32 s2, v252, 2
	v_readlane_b32 s3, v252, 3
	s_and_b64 s[2:3], s[0:1], s[2:3]
	s_mov_b64 exec, s[2:3]
	s_cbranch_execz .LBB0_741
	s_add_i32 s2, 0, 0x20040
	v_mov_b32_e32 v0, s2
	s_waitcnt vmcnt(0) expcnt(0) lgkmcnt(0)
	ds_read_b32 v2, v0
	s_add_i32 s2, 0, 0x20044
	v_mov_b32_e32 v0, s2
	ds_read_b32 v0, v0
	s_waitcnt lgkmcnt(1)
	v_cmp_ne_u32_e32 vcc, 0, v2
	s_cbranch_vccnz .LBB0_705
	s_add_u32 s4, s88, 0x1000
	s_addc_u32 s5, s89, 0
	s_add_u32 s6, s88, 0x1100
	s_addc_u32 s7, s89, 0
	s_add_u32 s8, s88, 0x1200
	v_readlane_b32 s2, v252, 0
	s_addc_u32 s9, s89, 0
	s_mul_i32 s2, s91, s2
	s_add_u32 s10, s88, 0x1300
	s_mul_i32 s2, s2, s90
	s_addc_u32 s11, s89, 0
	s_mov_b32 s3, 1
	v_mov_b32_e32 v16, 0
	s_branch .LBB0_693
